# k5 + FoX loop: decay-bias LDS reads issued with the K fragment reads and consumed after the QK MFMA chain
# speedup vs baseline: 1.0065x; 1.0030x over previous
; template <int DK, int MODE, bool OUTF32> ...
;     ...
;             const unsigned char* kb = a_lds + cur * KBUF + (32 * kh + c) * KP + hi * 16;
;             constexpr bool HOISTK = true;
;             bf16x8 kf[NKS];
;             if (HOISTK) {
; #pragma unroll
;                 for (int s = 0; s < NKS; ++s) kf[s] = *(const bf16x8*)(kb + s * 32);
;             }
;             const unsigned char* vb = a_lds + OFF_V + cur * VBUF + c * VP + (32 * kh + 4 * hi) * 2;
;             bf16x8 vf[8];
;     ...
;             constexpr bool HOISTV = (DK == 128) && (MODE == 2 || MODE == 1);
;             if (HOISTV) A_VREADS(0, 3);
;             if (HOISTK) __builtin_amdgcn_sched_barrier(0);
; #pragma unroll
;             for (int s = 0; s < NKS; ++s) p = __builtin_amdgcn_mfma_f32_32x32x16_bf16(HOISTK ? kf[s] : *(const bf16x8*)(kb + s * 32), qf[s], p, 0, 0, 0);
;             if (HOISTV) { A_VREADS(3, 4); __builtin_amdgcn_sched_barrier(0); }
;             if (MODE == 0) {
;                 const float* ckp = (const float*)(a_lds + OFF_CK + cur * 256) + 32 * kh + 4 * hi;
; #pragma unroll
;                 for (int g = 0; g < 4; ++g) {
;                     const float4 ck = *(const float4*)(ckp + 8 * g);
;                     p[4 * g + 0] = fmaf(p[4 * g + 0], sc2, cq - ck.x); p[4 * g + 1] = fmaf(p[4 * g + 1], sc2, cq - ck.y);
;                     p[4 * g + 2] = fmaf(p[4 * g + 2], sc2, cq - ck.z); p[4 * g + 3] = fmaf(p[4 * g + 3], sc2, cq - ck.w);
;                 }
.LBB0_282:
	s_or_b64 exec, exec, s[12:13]
	v_add_u32_e32 v186, s14, v181
	s_and_b32 s16, s15, 1
	v_cmp_le_i32_e32 vcc, v186, v182
	s_and_saveexec_b64 s[46:47], vcc
	s_cbranch_execz .LBB0_288
	s_mul_i32 s17, s16, 0x4400
	v_add_u32_e32 v88, s17, v177
	v_lshl_add_u32 v187, s16, 8, v173
	ds_read_b128 v[84:87], v88
	ds_read_b128 v[188:191], v88 offset:32
	ds_read_b128 v[208:211], v88 offset:64
	ds_read_b128 v[212:215], v88 offset:96
	ds_read_b128 v[216:219], v88 offset:128
	ds_read_b128 v[220:223], v88 offset:160
	ds_read_b128 v[224:227], v88 offset:192
	ds_read_b128 v[228:231], v88 offset:224
	ds_read_b128 v[234:237], v187
	ds_read_b128 v[238:241], v187 offset:32
	ds_read_b128 v[242:245], v187 offset:64
	ds_read_b128 v[252:255], v187 offset:96
	s_waitcnt lgkmcnt(11)
	v_mfma_f32_32x32x16_bf16 v[84:99], v[84:87], v[128:131], 0
	v_add_u32_e32 v186, 31, v186
	v_cmp_gt_i32_e32 vcc, v186, v159
	s_waitcnt lgkmcnt(10)
	v_mfma_f32_32x32x16_bf16 v[84:99], v[188:191], v[124:127], v[84:99]
	s_waitcnt lgkmcnt(9)
	v_mfma_f32_32x32x16_bf16 v[84:99], v[208:211], v[120:123], v[84:99]
	s_waitcnt lgkmcnt(8)
	v_mfma_f32_32x32x16_bf16 v[84:99], v[212:215], v[112:115], v[84:99]
	s_waitcnt lgkmcnt(7)
	v_mfma_f32_32x32x16_bf16 v[84:99], v[216:219], v[116:119], v[84:99]
	s_waitcnt lgkmcnt(6)
	v_mfma_f32_32x32x16_bf16 v[84:99], v[220:223], v[108:111], v[84:99]
	s_waitcnt lgkmcnt(5)
	v_mfma_f32_32x32x16_bf16 v[84:99], v[224:227], v[104:107], v[84:99]
	s_waitcnt lgkmcnt(4)
	v_mfma_f32_32x32x16_bf16 v[84:99], v[228:231], v[100:103], v[84:99]
	s_waitcnt lgkmcnt(0)
	v_sub_f32_e32 v193, v1, v235
	v_sub_f32_e32 v192, v68, v234
	v_sub_f32_e32 v197, v77, v237
	v_sub_f32_e32 v196, v78, v236
	v_sub_f32_e32 v213, v75, v239
	v_sub_f32_e32 v212, v76, v238
	v_sub_f32_e32 v215, v73, v241
	v_sub_f32_e32 v214, v70, v240
	v_sub_f32_e32 v189, v69, v243
	v_sub_f32_e32 v188, v72, v242
	v_sub_f32_e32 v191, v71, v245
	v_sub_f32_e32 v190, v74, v244
	v_sub_f32_e32 v209, v79, v253
	v_sub_f32_e32 v208, v80, v252
	v_sub_f32_e32 v211, v81, v255
	v_sub_f32_e32 v210, v82, v254
	v_add_u32_e32 v246, s17, v170
	v_add_u32_e32 v247, 0xc800, v246
	v_add_u32_e32 v250, 0xd800, v246
	v_add_u32_e32 v251, 0xe800, v246
	v_add_u32_e32 v246, 0xf800, v246
	ds_read2_b64 v[234:237], v247 offset1:2
	ds_read2_b64 v[238:241], v247 offset0:4 offset1:6
	ds_read2_b64 v[242:245], v250 offset0:32 offset1:34
	ds_read2_b64 v[252:255], v250 offset0:36 offset1:38
	ds_read2_b64 v[224:227], v251 offset0:64 offset1:66
	ds_read2_b64 v[228:231], v251 offset0:68 offset1:70
	ds_read2_b64 v[216:219], v246 offset0:96 offset1:98
	ds_read2_b64 v[220:223], v246 offset0:100 offset1:102
	s_nop 1
	v_pk_fma_f32 v[98:99], v[98:99], s[24:25], v[210:211] op_sel_hi:[1,0,1]
	v_pk_fma_f32 v[96:97], v[96:97], s[24:25], v[208:209] op_sel_hi:[1,0,1]
	v_pk_fma_f32 v[94:95], v[94:95], s[24:25], v[190:191] op_sel_hi:[1,0,1]
	v_pk_fma_f32 v[92:93], v[92:93], s[24:25], v[188:189] op_sel_hi:[1,0,1]
	v_pk_fma_f32 v[90:91], v[90:91], s[24:25], v[214:215] op_sel_hi:[1,0,1]
	v_pk_fma_f32 v[88:89], v[88:89], s[24:25], v[212:213] op_sel_hi:[1,0,1]
	v_pk_fma_f32 v[86:87], v[86:87], s[24:25], v[196:197] op_sel_hi:[1,0,1]
	v_pk_fma_f32 v[84:85], v[84:85], s[24:25], v[192:193] op_sel_hi:[1,0,1]
	s_and_saveexec_b64 s[12:13], vcc
	s_cbranch_execz .LBB0_285
	v_add_u32_e32 v186, s14, v183
	v_cmp_lt_i32_e32 vcc, v186, v154
	v_add_u32_e32 v187, 2, v186
	s_nop 0
	v_cndmask_b32_e32 v85, v206, v85, vcc
	v_cmp_le_i32_e32 vcc, v186, v154
	s_nop 1
	v_cndmask_b32_e32 v84, v206, v84, vcc
	v_cmp_le_i32_e32 vcc, v187, v154
	v_add_u32_e32 v187, 3, v186
	s_nop 0
	v_cndmask_b32_e32 v86, v206, v86, vcc
	v_cmp_le_i32_e32 vcc, v187, v154
	v_add_u32_e32 v187, 8, v186
	s_nop 0
	v_cndmask_b32_e32 v87, v206, v87, vcc
	v_cmp_le_i32_e32 vcc, v187, v154
	v_add_u32_e32 v187, 9, v186
	s_nop 0
	v_cndmask_b32_e32 v88, v206, v88, vcc
	v_cmp_le_i32_e32 vcc, v187, v154
	v_add_u32_e32 v187, 10, v186
	s_nop 0
	v_cndmask_b32_e32 v89, v206, v89, vcc
	v_cmp_le_i32_e32 vcc, v187, v154
	v_add_u32_e32 v187, 11, v186
	s_nop 0
	v_cndmask_b32_e32 v90, v206, v90, vcc
	v_cmp_le_i32_e32 vcc, v187, v154
	v_add_u32_e32 v187, 16, v186
	s_nop 0
	v_cndmask_b32_e32 v91, v206, v91, vcc
	v_cmp_le_i32_e32 vcc, v187, v154
	v_add_u32_e32 v187, 17, v186
	s_nop 0
	v_cndmask_b32_e32 v92, v206, v92, vcc
	v_cmp_le_i32_e32 vcc, v187, v154
	v_add_u32_e32 v187, 18, v186
	s_nop 0
	v_cndmask_b32_e32 v93, v206, v93, vcc
	v_cmp_le_i32_e32 vcc, v187, v154
	v_add_u32_e32 v187, 19, v186
	s_nop 0
	v_cndmask_b32_e32 v94, v206, v94, vcc
	v_cmp_le_i32_e32 vcc, v187, v154
	v_add_u32_e32 v187, 24, v186
	s_nop 0
	v_cndmask_b32_e32 v95, v206, v95, vcc
	v_cmp_le_i32_e32 vcc, v187, v154
	v_add_u32_e32 v187, 25, v186
	s_nop 0
	v_cndmask_b32_e32 v96, v206, v96, vcc
	v_cmp_le_i32_e32 vcc, v187, v154
	v_add_u32_e32 v187, 26, v186
	v_add_u32_e32 v186, 27, v186
	v_cndmask_b32_e32 v97, v206, v97, vcc
	v_cmp_le_i32_e32 vcc, v187, v154
	s_nop 1
	v_cndmask_b32_e32 v98, v206, v98, vcc
	v_cmp_le_i32_e32 vcc, v186, v154
	s_nop 1
	v_cndmask_b32_e32 v99, v206, v99, vcc
